# phase-5 queue: next ticket fetched at the start of each unit's store tail, dispatcher waits vmcnt(8) (flag-guarded fallback)
# baseline (speedup 1.0000x reference)
; #define CASE(k) if (PH_ON(k) && ph_lo <= (k) && (k) < ph_hi)
; __global__ void __launch_bounds__(512, 2) mega(Params p) {
;     ...
;         CASE(5) {
;             float lam;
;             { const int lane = threadIdx.x & 63; const float a = wave_sum(p.in[12][lane] * p.in[13][lane]), c = wave_sum(p.in[14][lane] * p.in[15][lane]); lam = expf(a) - expf(c) + 0.2f; }
;             unsigned* ctr = (unsigned*)(ws + O_CTR) + 4 * rep5;
;             constexpr int NU_S = 128, NU_P = 1024, NU_G = (256 + 32) * 4;
;             for (;;) {
;                 int u = queue_next(ctr, lds);
.LBB0_866:
	s_cmp_lt_i32 s54, 6
	s_cselect_b64 s[0:1], -1, 0
	s_cmp_gt_i32 s55, 5
	s_cselect_b64 s[4:5], -1, 0
	s_and_b64 s[0:1], s[0:1], s[4:5]
	s_andn2_b64 vcc, exec, s[0:1]
	s_cbranch_vccnz .LBB0_1019
	v_readlane_b32 s0, v252, 1
	v_readlane_b32 s1, v252, 2
	s_load_dwordx8 s[8:15], s[0:1], 0x60
	v_and_b32_e32 v0, 63, v208
	v_lshlrev_b32_e32 v0, 2, v0
	s_load_dwordx2 s[4:5], s[0:1], 0x90
	s_load_dwordx4 s[24:27], s[0:1], 0x10
	s_waitcnt lgkmcnt(0)
	global_load_dword v2, v0, s[8:9]
	global_load_dword v3, v0, s[10:11]
	global_load_dword v4, v0, s[12:13]
	global_load_dword v5, v0, s[14:15]
	v_mbcnt_lo_u32_b32 v0, -1, 0
	v_mbcnt_hi_u32_b32 v0, -1, v0
	v_and_b32_e32 v7, 64, v0
	v_xor_b32_e32 v8, 1, v0
	v_add_u32_e32 v7, 64, v7
	v_xor_b32_e32 v9, 2, v0
	v_cmp_lt_i32_e32 vcc, v8, v7
	v_xor_b32_e32 v10, 4, v0
	v_xor_b32_e32 v11, 8, v0
	v_cndmask_b32_e32 v8, v0, v8, vcc
	v_cmp_lt_i32_e32 vcc, v9, v7
	v_xor_b32_e32 v12, 16, v0
	v_xor_b32_e32 v13, 32, v0
	v_cndmask_b32_e32 v9, v0, v9, vcc
	v_cmp_lt_i32_e32 vcc, v10, v7
	v_writelane_b32 v252, s4, 10
	v_mov_b32_e32 v6, 0x7f800000
	v_cndmask_b32_e32 v10, v0, v10, vcc
	v_cmp_lt_i32_e32 vcc, v11, v7
	v_writelane_b32 v252, s5, 11
	s_load_dwordx4 s[16:19], s[0:1], 0x80
	s_load_dwordx4 s[20:23], s[0:1], 0x110
	s_load_dwordx2 s[4:5], s[0:1], 0xa0
	v_cndmask_b32_e32 v11, v0, v11, vcc
	v_cmp_lt_i32_e32 vcc, v12, v7
	s_mov_b32 s0, 0x3fb8aa3b
	s_waitcnt lgkmcnt(0)
	s_add_u32 s60, s22, 0x246a1000
	v_cndmask_b32_e32 v12, v0, v12, vcc
	v_cmp_lt_i32_e32 vcc, v13, v7
	v_lshlrev_b32_e32 v7, 2, v8
	v_lshlrev_b32_e32 v8, 2, v9
	v_lshlrev_b32_e32 v9, 2, v10
	v_lshlrev_b32_e32 v10, 2, v11
	v_cndmask_b32_e32 v0, v0, v13, vcc
	v_lshlrev_b32_e32 v171, 2, v0
	v_lshlrev_b32_e32 v12, 2, v12
	s_addc_u32 s61, s23, 0
	s_add_u32 s62, s22, 0x3001000
	s_addc_u32 s63, s23, 0
	s_add_u32 s64, s22, 0x2f933000
	s_addc_u32 s65, s23, 0
	s_add_u32 s66, s22, 0x267a1000
	s_addc_u32 s67, s23, 0
	s_add_u32 s68, s20, 0x12800000
	v_writelane_b32 v252, s4, 8
	s_addc_u32 s69, s21, 0
	s_add_u32 s70, s22, 0x1e3a1000
	v_writelane_b32 v252, s5, 9
	s_mov_b32 s4, 0xc2ce8ed0
	s_addc_u32 s71, s23, 0
	s_mov_b32 s1, 0x42b17218
	s_add_u32 s72, s22, 0x204a1000
	s_addc_u32 s73, s23, 0
	s_add_u32 s74, s22, 0x225a1000
	s_addc_u32 s75, s23, 0
	s_add_u32 s76, s22, 0x2a9a1000
	s_mov_b32 s38, -2.0
	s_mov_b32 s46, 0xc1000000
	s_mov_b32 s48, 0xc1200000
	s_mov_b32 s50, 0xc1800000
	s_addc_u32 s77, s23, 0
	s_mov_b32 s78, 0xc1900000
	s_mov_b32 s80, 0xc1c00000
	s_mov_b32 s82, 0xc1d00000
	s_mov_b32 s31, 0
	v_mov_b32_e32 v165, 1
	v_mov_b32_e32 v1, 0
	s_mov_b32 s35, 0xf800000
	v_mov_b32_e32 v170, 0x260
	s_movk_i32 s88, 0x140
	s_mov_b32 s89, 0x2a9a1000
	s_movk_i32 s90, 0x90
	s_mov_b32 s39, 0xc0400000
	s_mov_b32 s47, 0xc1100000
	s_mov_b32 s49, 0xc1300000
	s_mov_b32 s51, 0xc1880000
	s_mov_b32 s79, 0xc1980000
	s_mov_b32 s81, 0xc1c80000
	s_mov_b32 s83, 0xc1d80000
	s_waitcnt vmcnt(0)
	v_mul_f32_e32 v11, v2, v3
	ds_bpermute_b32 v11, v7, v11
	v_mul_f32_e32 v13, v4, v5
	ds_bpermute_b32 v7, v7, v13
	v_mov_b32_e32 v172, 0x3727c5ac
	v_mov_b32_e32 v174, 0xf149f2ca
	s_waitcnt lgkmcnt(1)
	v_fmac_f32_e32 v11, v2, v3
	ds_bpermute_b32 v0, v8, v11
	s_waitcnt lgkmcnt(1)
	v_fmac_f32_e32 v7, v4, v5
	ds_bpermute_b32 v2, v8, v7
	s_waitcnt lgkmcnt(1)
	v_add_f32_e32 v0, v11, v0
	ds_bpermute_b32 v3, v9, v0
	s_waitcnt lgkmcnt(1)
	v_add_f32_e32 v2, v7, v2
	ds_bpermute_b32 v4, v9, v2
	s_waitcnt lgkmcnt(1)
	v_add_f32_e32 v0, v0, v3
	ds_bpermute_b32 v3, v10, v0
	s_waitcnt lgkmcnt(1)
	v_add_f32_e32 v2, v2, v4
	ds_bpermute_b32 v4, v10, v2
	s_waitcnt lgkmcnt(1)
	v_add_f32_e32 v0, v0, v3
	ds_bpermute_b32 v3, v12, v0
	s_waitcnt lgkmcnt(1)
	v_add_f32_e32 v2, v2, v4
	ds_bpermute_b32 v4, v12, v2
	s_waitcnt lgkmcnt(1)
	v_add_f32_e32 v0, v0, v3
	ds_bpermute_b32 v3, v171, v0
	s_waitcnt lgkmcnt(1)
	v_add_f32_e32 v2, v2, v4
	ds_bpermute_b32 v4, v171, v2
	s_waitcnt lgkmcnt(1)
	v_add_f32_e32 v0, v0, v3
	v_mul_f32_e32 v3, 0x3fb8aa3b, v0
	s_waitcnt lgkmcnt(0)
	v_add_f32_e32 v2, v2, v4
	v_mul_f32_e32 v4, 0x3fb8aa3b, v2
	v_fma_f32 v5, v0, s0, -v3
	v_rndne_f32_e32 v7, v3
	v_fma_f32 v8, v2, s0, -v4
	v_rndne_f32_e32 v9, v4
	v_fmac_f32_e32 v5, 0x32a5705f, v0
	v_sub_f32_e32 v3, v3, v7
	v_fmac_f32_e32 v8, 0x32a5705f, v2
	v_sub_f32_e32 v4, v4, v9
	v_add_f32_e32 v3, v3, v5
	v_cvt_i32_f32_e32 v7, v7
	v_add_f32_e32 v4, v4, v8
	v_exp_f32_e32 v3, v3
	v_cvt_i32_f32_e32 v9, v9
	v_exp_f32_e32 v4, v4
	v_cmp_ngt_f32_e32 vcc, s4, v0
	v_ldexp_f32 v3, v3, v7
	s_add_i32 s0, 0, 0x23f00
	v_ldexp_f32 v4, v4, v9
	v_cndmask_b32_e32 v3, 0, v3, vcc
	v_cmp_ngt_f32_e32 vcc, s4, v2
	v_mov_b32_e32 v173, s0
	s_nop 0
	v_cndmask_b32_e32 v4, 0, v4, vcc
	v_cmp_nlt_f32_e32 vcc, s1, v0
	s_nop 1
	v_cndmask_b32_e32 v0, v6, v3, vcc
	v_cmp_nlt_f32_e32 vcc, s1, v2
	s_mov_b32 s1, 0x3f4ccccd
	s_nop 0
	v_cndmask_b32_e32 v2, v6, v4, vcc
	v_sub_f32_e32 v0, v0, v2
	v_add_f32_e32 v160, 0x3e4ccccd, v0
	v_mov_b32_e32 v161, v160
	v_mov_b32_e32 v249, 0
	s_branch .LBB0_871

; #define LAS __attribute__((address_space(3)))
; __device__ __forceinline__ int queue_next(unsigned* ctr, LAS unsigned char* lds) {
;     volatile LAS unsigned* w = (volatile LAS unsigned*)(lds + LDS_CTL);
;     if (threadIdx.x == 0) w[0] = atomicAdd(ctr, 1u);
;     __syncthreads();
;     const int u = (int)w[0];
;     __syncthreads();
;     return u;
.LBB0_871:
	s_mov_b64 s[6:7], exec
	v_readlane_b32 s4, v252, 6
	v_readlane_b32 s5, v252, 7
	s_and_b64 s[4:5], s[6:7], s[4:5]
	s_mov_b64 exec, s[4:5]
	s_cbranch_execz .LBB0_873
	v_cmp_eq_u32_e32 vcc, 1, v249
	s_cbranch_vccz .Lq5f_sync
	s_waitcnt vmcnt(8)
	v_mov_b32_e32 v0, v250
	s_branch .Lq5f_pub
.Lq5f_sync:
	s_waitcnt vmcnt(7)
	v_mov_b64_e32 v[2:3], s[52:53]
	flat_atomic_add v0, v[2:3], v165 sc0
	s_waitcnt vmcnt(0) lgkmcnt(0)
.Lq5f_pub:
	v_mov_b32_e32 v249, 0
	v_mov_b32_e32 v2, s0
	ds_write_b32 v2, v0

; #define GASP __attribute__((address_space(1)))
; __device__ __forceinline__ s16x4 vtr(const LAS unsigned char* p) { return __builtin_bit_cast(s16x4, __builtin_amdgcn_ds_read_tr16_b64_v4i16((LAS v4i16_t*)p)); }
; __device__ __forceinline__ bf16x8 cat8(s16x4 lo, s16x4 hi) { return (bf16x8){lo[0], lo[1], lo[2], lo[3], hi[0], hi[1], hi[2], hi[3]}; }
; __device__ __forceinline__ void gate_unit(const Params& p, LAS unsigned char* L, int row0, int n, int g, int sample_b) {
;     ...
;         for (int ks = 0; ks < 8; ++ks) if (ks < nks) {
; #pragma unroll
;             for (int db = 0; db < 2; ++db) {
;                 const s16x4 lo = vtr(L + vlane_off + (ks * 16) * DA_VRS + db * 64), hi4 = vtr(L + vlane_off + (ks * 16 + 4) * DA_VRS + db * 64);
;                 OT[db] = __builtin_amdgcn_mfma_f32_32x32x16_bf16(cat8(lo, hi4), wf[ks], OT[db], 0, 0, 0);
;             }
;         }
;         bf16_t* op = (bf16_t*)(ws + O_MIX) + (size_t)(row0 + te) * D + 512 + g * 128 + dh * 64 + 4 * hi;
; #pragma unroll
;         for (int db = 0; db < 2; ++db)
; #pragma unroll
;             for (int g4 = 0; g4 < 4; ++g4) { const u32x2 u2 = uu[db * 4 + g4];
;                 const float u0 = __uint_as_float(u2.x << 16), u1 = __uint_as_float(u2.x & 0xffff0000u), u2f = __uint_as_float(u2.y << 16), u3 = __uint_as_float(u2.y & 0xffff0000u);
;                 u32x2 w; w.x = pk2(u0 * (OT[db][4 * g4] + bias), u1 * (OT[db][4 * g4 + 1] + bias)); w.y = pk2(u2f * (OT[db][4 * g4 + 2] + bias), u3 * (OT[db][4 * g4 + 3] + bias));
;                 *(GASP u32x2*)(op + db * 32 + 8 * g4) = w; }
.LBB0_886:
	s_or_b64 exec, exec, s[10:11]
	s_and_b64 vcc, exec, s[6:7]
	s_waitcnt lgkmcnt(0)
	s_barrier
	s_cbranch_vccnz .LBB0_888
	v_lshrrev_b32_e32 v0, 2, v61
	s_waitcnt vmcnt(7)
	v_and_b32_e32 v2, 16, v61
	v_lshlrev_b32_e32 v3, 2, v61
	v_and_or_b32 v0, v0, 3, v76
	v_and_or_b32 v2, v3, 12, v2
	v_lshlrev_b32_e32 v2, 1, v2
	s_lshl_b32 s6, s13, 7
	v_mad_u32_u24 v0, v0, s88, 0
	v_add3_u32 v0, v0, v2, s6
	ds_read_b64_tr_b16 v[2:3], v0
	ds_read_b64_tr_b16 v[4:5], v0 offset:1280
	s_waitcnt vmcnt(6)
	ds_read_b64_tr_b16 v[8:9], v0 offset:1344
	ds_read_b64_tr_b16 v[6:7], v0 offset:64
	s_waitcnt vmcnt(0) lgkmcnt(2)
	v_mfma_f32_32x32x16_bf16 v[18:33], v[2:5], v[14:17], 0
	ds_read_b64_tr_b16 v[38:39], v0 offset:5120
	ds_read_b64_tr_b16 v[40:41], v0 offset:6400
	ds_read_b64_tr_b16 v[44:45], v0 offset:6464
	ds_read_b64_tr_b16 v[42:43], v0 offset:5184
	v_or_b32_e32 v0, s12, v88
	v_lshlrev_b32_e32 v0, 11, v0
	v_lshl_add_u64 v[46:47], s[22:23], 0, v[0:1]
	v_mov_b32_e32 v59, v1
	s_lshl_b32 s6, s13, 6
	s_ashr_i32 s7, s6, 31
	s_waitcnt lgkmcnt(4)
	v_mfma_f32_32x32x16_bf16 v[2:17], v[6:9], v[14:17], 0
	v_mov_b32_e32 v77, v1
	s_waitcnt lgkmcnt(2)
	v_mfma_f32_32x32x16_bf16 v[18:33], v[38:41], v[34:37], v[18:33]
	v_lshl_add_u64 v[38:39], v[58:59], 1, v[46:47]
	v_lshl_add_u64 v[38:39], s[6:7], 1, v[38:39]
	v_lshl_add_u64 v[38:39], v[38:39], 0, v[76:77]
	s_mov_b64 s[6:7], 0x2a9a1400
	s_waitcnt lgkmcnt(0)
	v_mfma_f32_32x32x16_bf16 v[2:17], v[42:45], v[34:37], v[2:17]
	v_lshlrev_b32_e32 v36, 16, v80
	v_and_b32_e32 v37, 0xffff0000, v80
	s_nop 3
	v_add_f32_e64 v18, v60, v18
	v_add_f32_e64 v19, v60, v19
	v_mul_f32_e64 v18, v18, v36
	v_mul_f32_e64 v19, v19, v37
	v_lshlrev_b32_e32 v36, 16, v81
	v_and_b32_e32 v37, 0xffff0000, v81
	v_pk_add_f32 v[20:21], v[60:61], v[20:21] op_sel_hi:[0,1]
	v_pk_mul_f32 v[20:21], v[20:21], v[36:37]
	v_cvt_pk_bf16_f32 v18, v18, v19
	v_cvt_pk_bf16_f32 v19, v20, v21
	v_add_co_u32_e32 v20, vcc, s89, v38
	v_lshl_add_u64 v[34:35], v[38:39], 0, s[6:7]
	s_nop 0
	v_addc_co_u32_e32 v21, vcc, 0, v39, vcc
	s_mov_b64 s[100:101], exec
	v_cmp_eq_u32_e64 s[98:99], 0, v208
	s_and_b64 s[98:99], s[100:101], s[98:99]
	s_mov_b64 exec, s[98:99]
	s_cbranch_execz .Lq5s_g1
	v_mov_b32_e32 v251, 0
	v_mov_b32_e32 v249, 1
	global_atomic_add v250, v251, v165, s[52:53] sc0
.Lq5s_g1:
	s_mov_b64 exec, s[100:101]
	global_store_dwordx2 v[20:21], v[18:19], off offset:1024
	v_lshlrev_b32_e32 v18, 16, v78
	v_and_b32_e32 v19, 0xffff0000, v78
	v_pk_add_f32 v[20:21], v[60:61], v[22:23] op_sel_hi:[0,1]
	v_pk_mul_f32 v[18:19], v[20:21], v[18:19]
	v_lshlrev_b32_e32 v20, 16, v79
	v_and_b32_e32 v21, 0xffff0000, v79
	v_pk_add_f32 v[22:23], v[60:61], v[24:25] op_sel_hi:[0,1]
	v_pk_mul_f32 v[20:21], v[22:23], v[20:21]
	v_cvt_pk_bf16_f32 v18, v18, v19
	v_cvt_pk_bf16_f32 v19, v20, v21
	global_store_dwordx2 v[34:35], v[18:19], off offset:16
	v_lshlrev_b32_e32 v18, 16, v72
	v_and_b32_e32 v19, 0xffff0000, v72
	v_pk_add_f32 v[20:21], v[60:61], v[26:27] op_sel_hi:[0,1]
	v_pk_mul_f32 v[18:19], v[20:21], v[18:19]
	v_lshlrev_b32_e32 v20, 16, v73
	v_and_b32_e32 v21, 0xffff0000, v73
	v_pk_add_f32 v[22:23], v[60:61], v[28:29] op_sel_hi:[0,1]
	v_pk_mul_f32 v[20:21], v[22:23], v[20:21]
	v_cvt_pk_bf16_f32 v18, v18, v19
	v_cvt_pk_bf16_f32 v19, v20, v21
	global_store_dwordx2 v[34:35], v[18:19], off offset:32
	v_lshlrev_b32_e32 v18, 16, v70
	v_and_b32_e32 v19, 0xffff0000, v70
	v_pk_add_f32 v[20:21], v[60:61], v[30:31] op_sel_hi:[0,1]
	v_pk_mul_f32 v[18:19], v[20:21], v[18:19]
	v_lshlrev_b32_e32 v20, 16, v71
	v_and_b32_e32 v21, 0xffff0000, v71
	v_pk_add_f32 v[22:23], v[60:61], v[32:33] op_sel_hi:[0,1]
	v_pk_mul_f32 v[20:21], v[22:23], v[20:21]
	v_cvt_pk_bf16_f32 v18, v18, v19
	v_cvt_pk_bf16_f32 v19, v20, v21
	global_store_dwordx2 v[34:35], v[18:19], off offset:48
	v_lshlrev_b32_e32 v18, 16, v68
	v_and_b32_e32 v19, 0xffff0000, v68
	v_pk_add_f32 v[2:3], v[60:61], v[2:3] op_sel_hi:[0,1]
	v_pk_mul_f32 v[2:3], v[2:3], v[18:19]
	v_lshlrev_b32_e32 v18, 16, v69
	v_and_b32_e32 v19, 0xffff0000, v69
	v_pk_add_f32 v[4:5], v[60:61], v[4:5] op_sel_hi:[0,1]
	v_pk_mul_f32 v[4:5], v[4:5], v[18:19]
	v_cvt_pk_bf16_f32 v2, v2, v3
	v_cvt_pk_bf16_f32 v3, v4, v5
	global_store_dwordx2 v[34:35], v[2:3], off offset:64
	v_lshlrev_b32_e32 v2, 16, v66
	v_and_b32_e32 v3, 0xffff0000, v66
	v_pk_add_f32 v[4:5], v[60:61], v[6:7] op_sel_hi:[0,1]
	v_pk_mul_f32 v[2:3], v[4:5], v[2:3]
	v_lshlrev_b32_e32 v4, 16, v67
	v_and_b32_e32 v5, 0xffff0000, v67
	v_pk_add_f32 v[6:7], v[60:61], v[8:9] op_sel_hi:[0,1]
	v_pk_mul_f32 v[4:5], v[6:7], v[4:5]
	v_cvt_pk_bf16_f32 v2, v2, v3
	v_cvt_pk_bf16_f32 v3, v4, v5
	global_store_dwordx2 v[34:35], v[2:3], off offset:80
	v_lshlrev_b32_e32 v2, 16, v64
	v_and_b32_e32 v3, 0xffff0000, v64
	v_pk_add_f32 v[4:5], v[60:61], v[10:11] op_sel_hi:[0,1]
	v_pk_mul_f32 v[2:3], v[4:5], v[2:3]
	v_lshlrev_b32_e32 v4, 16, v65
	v_and_b32_e32 v5, 0xffff0000, v65
	v_pk_add_f32 v[6:7], v[60:61], v[12:13] op_sel_hi:[0,1]
	v_pk_mul_f32 v[4:5], v[6:7], v[4:5]
	v_cvt_pk_bf16_f32 v2, v2, v3
	v_cvt_pk_bf16_f32 v3, v4, v5
	global_store_dwordx2 v[34:35], v[2:3], off offset:96
	v_lshlrev_b32_e32 v2, 16, v62
	v_and_b32_e32 v3, 0xffff0000, v62
	v_pk_add_f32 v[4:5], v[60:61], v[14:15] op_sel_hi:[0,1]
	v_pk_mul_f32 v[2:3], v[4:5], v[2:3]
	v_lshlrev_b32_e32 v4, 16, v63
	v_and_b32_e32 v5, 0xffff0000, v63
	v_pk_add_f32 v[6:7], v[60:61], v[16:17] op_sel_hi:[0,1]
	v_pk_mul_f32 v[4:5], v[6:7], v[4:5]
	v_cvt_pk_bf16_f32 v2, v2, v3
	v_cvt_pk_bf16_f32 v3, v4, v5
	global_store_dwordx2 v[34:35], v[2:3], off offset:112

; #define GASP __attribute__((address_space(1)))
; __device__ __forceinline__ void gate_unit(const Params& p, LAS unsigned char* L, int row0, int n, int g, int sample_b) {
;     ...
;         bf16_t* op = (bf16_t*)(ws + O_MIX) + (size_t)(row0 + te) * D + 512 + g * 128 + dh * 64 + 4 * hi;
; #pragma unroll
;         for (int db = 0; db < 2; ++db)
; #pragma unroll
;             for (int g4 = 0; g4 < 4; ++g4) { const u32x2 u2 = uu[db * 4 + g4];
;                 const float u0 = __uint_as_float(u2.x << 16), u1 = __uint_as_float(u2.x & 0xffff0000u), u2f = __uint_as_float(u2.y << 16), u3 = __uint_as_float(u2.y & 0xffff0000u);
;                 u32x2 w; w.x = pk2(u0 * (OT[db][4 * g4] + bias), u1 * (OT[db][4 * g4 + 1] + bias)); w.y = pk2(u2f * (OT[db][4 * g4 + 2] + bias), u3 * (OT[db][4 * g4 + 3] + bias));
;                 *(GASP u32x2*)(op + db * 32 + 8 * g4) = w; }
;     }
;     __syncthreads();
.LBB0_921:
	v_lshlrev_b32_e32 v34, 11, v106
	v_mov_b32_e32 v35, v1
	v_lshl_add_u64 v[34:35], s[22:23], 0, v[34:35]
	v_lshlrev_b32_e32 v36, 2, v83
	v_lshl_add_u64 v[34:35], v[0:1], 1, v[34:35]
	s_waitcnt vmcnt(7)
	v_lshlrev_b32_e32 v38, 16, v98
	v_and_b32_e32 v39, 0xffff0000, v98
	s_nop 1
	v_pk_add_f32 v[18:19], v[82:83], v[18:19] op_sel_hi:[0,1]
	v_lshl_add_u64 v[34:35], s[84:85], 1, v[34:35]
	v_lshlrev_b32_e32 v0, 1, v36
	v_pk_mul_f32 v[18:19], v[18:19], v[38:39]
	v_lshlrev_b32_e32 v38, 16, v99
	v_and_b32_e32 v39, 0xffff0000, v99
	v_pk_add_f32 v[20:21], v[82:83], v[20:21] op_sel_hi:[0,1]
	v_lshl_add_u64 v[34:35], v[34:35], 0, v[0:1]
	v_pk_mul_f32 v[20:21], v[20:21], v[38:39]
	v_cvt_pk_bf16_f32 v18, v18, v19
	v_cvt_pk_bf16_f32 v19, v20, v21
	v_add_co_u32_e32 v20, vcc, s89, v34
	s_mov_b64 s[6:7], 0x2a9a1400
	s_nop 0
	v_addc_co_u32_e32 v21, vcc, 0, v35, vcc
	s_mov_b64 s[100:101], exec
	v_cmp_eq_u32_e64 s[98:99], 0, v208
	s_and_b64 s[98:99], s[100:101], s[98:99]
	s_mov_b64 exec, s[98:99]
	s_cbranch_execz .Lq5s_g2
	v_mov_b32_e32 v251, 0
	v_mov_b32_e32 v249, 1
	global_atomic_add v250, v251, v165, s[52:53] sc0
.Lq5s_g2:
	s_mov_b64 exec, s[100:101]
	global_store_dwordx2 v[20:21], v[18:19], off offset:1024
	s_waitcnt vmcnt(7)
	v_lshlrev_b32_e32 v18, 16, v96
	v_and_b32_e32 v19, 0xffff0000, v96
	v_pk_add_f32 v[20:21], v[82:83], v[22:23] op_sel_hi:[0,1]
	v_pk_mul_f32 v[18:19], v[20:21], v[18:19]
	v_lshlrev_b32_e32 v20, 16, v97
	v_and_b32_e32 v21, 0xffff0000, v97
	v_pk_add_f32 v[22:23], v[82:83], v[24:25] op_sel_hi:[0,1]
	v_pk_mul_f32 v[20:21], v[22:23], v[20:21]
	v_lshl_add_u64 v[36:37], v[34:35], 0, s[6:7]
	v_cvt_pk_bf16_f32 v18, v18, v19
	v_cvt_pk_bf16_f32 v19, v20, v21
	global_store_dwordx2 v[36:37], v[18:19], off offset:16
	s_waitcnt vmcnt(7)
	v_lshlrev_b32_e32 v18, 16, v94
	v_and_b32_e32 v19, 0xffff0000, v94
	v_pk_add_f32 v[20:21], v[82:83], v[26:27] op_sel_hi:[0,1]
	v_pk_mul_f32 v[18:19], v[20:21], v[18:19]
	v_lshlrev_b32_e32 v20, 16, v95
	v_and_b32_e32 v21, 0xffff0000, v95
	v_pk_add_f32 v[22:23], v[82:83], v[28:29] op_sel_hi:[0,1]
	v_pk_mul_f32 v[20:21], v[22:23], v[20:21]
	v_cvt_pk_bf16_f32 v18, v18, v19
	v_cvt_pk_bf16_f32 v19, v20, v21
	global_store_dwordx2 v[36:37], v[18:19], off offset:32
	s_waitcnt vmcnt(7)
	v_lshlrev_b32_e32 v18, 16, v92
	v_and_b32_e32 v19, 0xffff0000, v92
	v_pk_add_f32 v[20:21], v[82:83], v[30:31] op_sel_hi:[0,1]
	v_pk_mul_f32 v[18:19], v[20:21], v[18:19]
	v_lshlrev_b32_e32 v20, 16, v93
	v_and_b32_e32 v21, 0xffff0000, v93
	v_pk_add_f32 v[22:23], v[82:83], v[32:33] op_sel_hi:[0,1]
	v_pk_mul_f32 v[20:21], v[22:23], v[20:21]
	v_cvt_pk_bf16_f32 v18, v18, v19
	v_cvt_pk_bf16_f32 v19, v20, v21
	global_store_dwordx2 v[36:37], v[18:19], off offset:48
	s_waitcnt vmcnt(7)
	v_lshlrev_b32_e32 v18, 16, v90
	v_and_b32_e32 v19, 0xffff0000, v90
	v_pk_add_f32 v[2:3], v[82:83], v[2:3] op_sel_hi:[0,1]
	v_pk_mul_f32 v[2:3], v[2:3], v[18:19]
	v_lshlrev_b32_e32 v18, 16, v91
	v_and_b32_e32 v19, 0xffff0000, v91
	v_pk_add_f32 v[4:5], v[82:83], v[4:5] op_sel_hi:[0,1]
	v_pk_mul_f32 v[4:5], v[4:5], v[18:19]
	v_cvt_pk_bf16_f32 v2, v2, v3
	v_cvt_pk_bf16_f32 v3, v4, v5
	global_store_dwordx2 v[36:37], v[2:3], off offset:64
	s_waitcnt vmcnt(7)
	v_lshlrev_b32_e32 v2, 16, v88
	v_and_b32_e32 v3, 0xffff0000, v88
	v_pk_add_f32 v[4:5], v[82:83], v[6:7] op_sel_hi:[0,1]
	v_pk_mul_f32 v[2:3], v[4:5], v[2:3]
	v_lshlrev_b32_e32 v4, 16, v89
	v_and_b32_e32 v5, 0xffff0000, v89
	v_pk_add_f32 v[6:7], v[82:83], v[8:9] op_sel_hi:[0,1]
	v_pk_mul_f32 v[4:5], v[6:7], v[4:5]
	v_cvt_pk_bf16_f32 v2, v2, v3
	v_cvt_pk_bf16_f32 v3, v4, v5
	global_store_dwordx2 v[36:37], v[2:3], off offset:80
	s_waitcnt vmcnt(7)
	v_lshlrev_b32_e32 v2, 16, v86
	v_and_b32_e32 v3, 0xffff0000, v86
	v_pk_add_f32 v[4:5], v[82:83], v[10:11] op_sel_hi:[0,1]
	v_pk_mul_f32 v[2:3], v[4:5], v[2:3]
	v_lshlrev_b32_e32 v4, 16, v87
	v_and_b32_e32 v5, 0xffff0000, v87
	v_pk_add_f32 v[6:7], v[82:83], v[12:13] op_sel_hi:[0,1]
	v_pk_mul_f32 v[4:5], v[6:7], v[4:5]
	v_cvt_pk_bf16_f32 v2, v2, v3
	v_cvt_pk_bf16_f32 v3, v4, v5
	global_store_dwordx2 v[36:37], v[2:3], off offset:96
	s_waitcnt vmcnt(7)
	v_lshlrev_b32_e32 v2, 16, v84
	v_and_b32_e32 v3, 0xffff0000, v84
	v_pk_add_f32 v[4:5], v[82:83], v[14:15] op_sel_hi:[0,1]
	v_pk_mul_f32 v[2:3], v[4:5], v[2:3]
	v_lshlrev_b32_e32 v4, 16, v85
	v_and_b32_e32 v5, 0xffff0000, v85
	v_pk_add_f32 v[6:7], v[82:83], v[16:17] op_sel_hi:[0,1]
	v_pk_mul_f32 v[4:5], v[6:7], v[4:5]
	v_cvt_pk_bf16_f32 v2, v2, v3
	v_cvt_pk_bf16_f32 v3, v4, v5
	global_store_dwordx2 v[36:37], v[2:3], off offset:112
	s_barrier
	s_mov_b64 s[6:7], 0

;     ...
;         __syncthreads();
;         if (map == 0) {
;             float ss = 0.f;
; #pragma unroll
;             for (int eb = 0; eb < 4; ++eb)
; #pragma unroll
;                 for (int rg = 0; rg < 16; ++rg) { const float o = OT[eb][rg] * inv - lam * X[(eb * 32 + (rg & 3) + 8 * (rg >> 2) + 4 * hi) * 32 + r]; OT[eb][rg] = o; ss += o * o; }
;             ss += __shfl_xor(ss, 32);
.LBB0_941:
	s_cmpk_gt_u32 s8, 0xff
	s_waitcnt lgkmcnt(0)
	s_barrier
	s_cbranch_scc1 .LBB0_943
	v_add_u32_e32 v67, 0x400, v66
	ds_read2_b32 v[70:71], v66 offset1:32
	ds_read2_b32 v[72:73], v66 offset0:64 offset1:96
	ds_read2_b32 v[74:75], v67 offset1:32
	ds_read2_b32 v[76:77], v67 offset0:64 offset1:96
	v_add_u32_e32 v67, 0x800, v66
	ds_read2_b32 v[84:85], v67 offset1:32
	ds_read2_b32 v[86:87], v67 offset0:64 offset1:96
	v_add_u32_e32 v67, 0xc00, v66
	ds_read2_b32 v[88:89], v67 offset1:32
	ds_read2_b32 v[90:91], v67 offset0:64 offset1:96
	v_add_u32_e32 v67, 0x1000, v66
	ds_read2_b32 v[92:93], v67 offset1:32
	ds_read2_b32 v[94:95], v67 offset0:64 offset1:96
	v_add_u32_e32 v67, 0x1400, v66
	ds_read2_b32 v[96:97], v67 offset1:32
	ds_read2_b32 v[98:99], v67 offset0:64 offset1:96
	v_add_u32_e32 v67, 0x1800, v66
	s_waitcnt lgkmcnt(11)
	v_pk_mul_f32 v[70:71], v[160:161], v[70:71]
	ds_read2_b32 v[100:101], v67 offset1:32
	ds_read2_b32 v[102:103], v67 offset0:64 offset1:96
	v_add_u32_e32 v67, 0x1c00, v66
	v_pk_fma_f32 v[70:71], v[50:51], v[0:1], v[70:71] op_sel_hi:[1,0,1] neg_lo:[0,0,1] neg_hi:[0,0,1]
	s_waitcnt lgkmcnt(10)
	v_pk_mul_f32 v[50:51], v[160:161], v[76:77]
	ds_read2_b32 v[104:105], v67 offset1:32
	ds_read2_b32 v[106:107], v67 offset0:64 offset1:96
	v_add_u32_e32 v67, 0x2000, v66
	v_pk_mul_f32 v[72:73], v[160:161], v[72:73]
	v_pk_fma_f32 v[50:51], v[56:57], v[0:1], v[50:51] op_sel_hi:[1,0,1] neg_lo:[0,0,1] neg_hi:[0,0,1]
	v_pk_mul_f32 v[56:57], v[160:161], v[74:75]
	ds_read2_b32 v[108:109], v67 offset1:32
	ds_read2_b32 v[110:111], v67 offset0:64 offset1:96
	v_add_u32_e32 v67, 0x2400, v66
	v_pk_fma_f32 v[52:53], v[52:53], v[0:1], v[72:73] op_sel_hi:[1,0,1] neg_lo:[0,0,1] neg_hi:[0,0,1]
	v_pk_fma_f32 v[72:73], v[54:55], v[0:1], v[56:57] op_sel_hi:[1,0,1] neg_lo:[0,0,1] neg_hi:[0,0,1]
	s_waitcnt lgkmcnt(13)
	v_pk_mul_f32 v[56:57], v[160:161], v[84:85]
	ds_read2_b32 v[112:113], v67 offset1:32
	s_waitcnt vmcnt(3)
	ds_read2_b32 v[114:115], v67 offset0:64 offset1:96
	v_add_u32_e32 v67, 0x2800, v66
	v_pk_fma_f32 v[74:75], v[58:59], v[0:1], v[56:57] op_sel_hi:[1,0,1] neg_lo:[0,0,1] neg_hi:[0,0,1]
	s_waitcnt lgkmcnt(13)
	v_pk_mul_f32 v[58:59], v[160:161], v[88:89]
	ds_read2_b32 v[116:117], v67 offset1:32
	s_waitcnt vmcnt(2)
	ds_read2_b32 v[118:119], v67 offset0:64 offset1:96
	v_add_u32_e32 v67, 0x2c00, v66
	v_pk_fma_f32 v[76:77], v[62:63], v[0:1], v[58:59] op_sel_hi:[1,0,1] neg_lo:[0,0,1] neg_hi:[0,0,1]
	s_waitcnt lgkmcnt(12)
	v_pk_mul_f32 v[58:59], v[160:161], v[94:95]
	ds_read2_b32 v[120:121], v67 offset1:32
	s_waitcnt vmcnt(1)
	ds_read2_b32 v[122:123], v67 offset0:64 offset1:96
	v_add_u32_e32 v67, 0x3000, v66
	v_pk_mul_f32 v[54:55], v[160:161], v[86:87]
	v_pk_fma_f32 v[58:59], v[36:37], v[0:1], v[58:59] op_sel_hi:[1,0,1] neg_lo:[0,0,1] neg_hi:[0,0,1]
	v_pk_mul_f32 v[36:37], v[160:161], v[92:93]
	ds_read2_b32 v[124:125], v67 offset1:32
	s_waitcnt vmcnt(0)
	ds_read2_b32 v[126:127], v67 offset0:64 offset1:96
	v_add_u32_e32 v67, 0x3400, v66
	v_add_u32_e32 v78, 0x3800, v66
	v_pk_fma_f32 v[54:55], v[60:61], v[0:1], v[54:55] op_sel_hi:[1,0,1] neg_lo:[0,0,1] neg_hi:[0,0,1]
	v_pk_fma_f32 v[60:61], v[34:35], v[0:1], v[36:37] op_sel_hi:[1,0,1] neg_lo:[0,0,1] neg_hi:[0,0,1]
	s_waitcnt lgkmcnt(14)
	v_pk_mul_f32 v[34:35], v[160:161], v[98:99]
	ds_read2_b32 v[128:129], v67 offset1:32
	ds_read2_b32 v[68:69], v78 offset0:64 offset1:96
	ds_read2_b32 v[130:131], v67 offset0:64 offset1:96
	ds_read2_b32 v[132:133], v78 offset1:32
	v_pk_fma_f32 v[34:35], v[40:41], v[0:1], v[34:35] op_sel_hi:[1,0,1] neg_lo:[0,0,1] neg_hi:[0,0,1]
	s_waitcnt lgkmcnt(14)
	v_pk_mul_f32 v[40:41], v[160:161], v[104:105]
	v_pk_mul_f32 v[36:37], v[160:161], v[96:97]
	v_pk_fma_f32 v[46:47], v[46:47], v[0:1], v[40:41] op_sel_hi:[1,0,1] neg_lo:[0,0,1] neg_hi:[0,0,1]
	s_waitcnt lgkmcnt(12)
	v_pk_mul_f32 v[40:41], v[160:161], v[110:111]
	v_pk_mul_f32 v[56:57], v[160:161], v[90:91]
	v_pk_fma_f32 v[62:63], v[38:39], v[0:1], v[36:37] op_sel_hi:[1,0,1] neg_lo:[0,0,1] neg_hi:[0,0,1]
	v_pk_mul_f32 v[38:39], v[160:161], v[100:101]
	v_pk_fma_f32 v[40:41], v[20:21], v[0:1], v[40:41] op_sel_hi:[1,0,1] neg_lo:[0,0,1] neg_hi:[0,0,1]
	v_pk_mul_f32 v[20:21], v[160:161], v[108:109]
	v_add_u32_e32 v78, 0x3c00, v66
	s_waitcnt lgkmcnt(2)
	v_pk_mul_f32 v[66:67], v[160:161], v[68:69]
	v_pk_fma_f32 v[56:57], v[64:65], v[0:1], v[56:57] op_sel_hi:[1,0,1] neg_lo:[0,0,1] neg_hi:[0,0,1]
	v_pk_mul_f32 v[36:37], v[160:161], v[102:103]
	v_pk_fma_f32 v[64:65], v[42:43], v[0:1], v[38:39] op_sel_hi:[1,0,1] neg_lo:[0,0,1] neg_hi:[0,0,1]
	v_pk_fma_f32 v[42:43], v[18:19], v[0:1], v[20:21] op_sel_hi:[1,0,1] neg_lo:[0,0,1] neg_hi:[0,0,1]
	v_pk_mul_f32 v[18:19], v[160:161], v[114:115]
	v_pk_mul_f32 v[20:21], v[160:161], v[112:113]
	ds_read2_b32 v[80:81], v78 offset1:32
	v_pk_fma_f32 v[66:67], v[12:13], v[0:1], v[66:67] op_sel_hi:[1,0,1] neg_lo:[0,0,1] neg_hi:[0,0,1]
	ds_read2_b32 v[12:13], v78 offset0:64 offset1:96
	v_pk_fma_f32 v[36:37], v[44:45], v[0:1], v[36:37] op_sel_hi:[1,0,1] neg_lo:[0,0,1] neg_hi:[0,0,1]
	v_pk_fma_f32 v[18:19], v[24:25], v[0:1], v[18:19] op_sel_hi:[1,0,1] neg_lo:[0,0,1] neg_hi:[0,0,1]
	v_pk_fma_f32 v[44:45], v[22:23], v[0:1], v[20:21] op_sel_hi:[1,0,1] neg_lo:[0,0,1] neg_hi:[0,0,1]
	v_pk_mul_f32 v[20:21], v[160:161], v[118:119]
	v_pk_mul_f32 v[24:25], v[160:161], v[120:121]
	v_pk_fma_f32 v[20:21], v[28:29], v[0:1], v[20:21] op_sel_hi:[1,0,1] neg_lo:[0,0,1] neg_hi:[0,0,1]
	v_pk_fma_f32 v[28:29], v[30:31], v[0:1], v[24:25] op_sel_hi:[1,0,1] neg_lo:[0,0,1] neg_hi:[0,0,1]
	v_pk_mul_f32 v[24:25], v[160:161], v[126:127]
	v_pk_mul_f32 v[22:23], v[160:161], v[116:117]
	v_pk_fma_f32 v[4:5], v[4:5], v[0:1], v[24:25] op_sel_hi:[1,0,1] neg_lo:[0,0,1] neg_hi:[0,0,1]
	v_pk_mul_f32 v[24:25], v[160:161], v[124:125]
	s_waitcnt lgkmcnt(1)
; #define GASP __attribute__((address_space(1)))
;     ...
;                 for (int rg = 0; rg < 16; ++rg) { const float o = OT[eb][rg] * inv - lam * X[(eb * 32 + (rg & 3) + 8 * (rg >> 2) + 4 * hi) * 32 + r]; OT[eb][rg] = o; ss += o * o; }
;             ss += __shfl_xor(ss, 32);
;             const float rms = 0.8f / sqrtf(ss * (1.f / 128.f) + LN_EPS);
;             const float* sg = p.in[16];
;             bf16_t* op = (bf16_t*)(ws + O_MIX) + (size_t)(rowq0 + r) * D + h * 128 + 4 * hi;
; #pragma unroll
;             for (int eb = 0; eb < 4; ++eb)
; #pragma unroll
;                 for (int g4 = 0; g4 < 4; ++g4) { const int e0 = eb * 32 + 8 * g4; const f32x4 gv = *(const GASP f32x4*)(sg + e0 + 4 * hi);
;                     u32x2 w; w.x = pk2(OT[eb][4 * g4] * rms * gv[0], OT[eb][4 * g4 + 1] * rms * gv[1]); w.y = pk2(OT[eb][4 * g4 + 2] * rms * gv[2], OT[eb][4 * g4 + 3] * rms * gv[3]);
;                     *(GASP u32x2*)(op + e0) = w; }
	v_pk_mul_f32 v[68:69], v[160:161], v[80:81]
	v_pk_fma_f32 v[24:25], v[2:3], v[0:1], v[24:25] op_sel_hi:[1,0,1] neg_lo:[0,0,1] neg_hi:[0,0,1]
	v_pk_mul_f32 v[2:3], v[160:161], v[130:131]
	s_waitcnt lgkmcnt(0)
	v_pk_mul_f32 v[12:13], v[160:161], v[12:13]
	v_pk_fma_f32 v[2:3], v[8:9], v[0:1], v[2:3] op_sel_hi:[1,0,1] neg_lo:[0,0,1] neg_hi:[0,0,1]
	v_pk_mul_f32 v[8:9], v[160:161], v[128:129]
	v_pk_mul_f32 v[136:137], v[70:71], v[70:71]
	v_pk_mul_f32 v[38:39], v[160:161], v[106:107]
	v_pk_fma_f32 v[26:27], v[26:27], v[0:1], v[22:23] op_sel_hi:[1,0,1] neg_lo:[0,0,1] neg_hi:[0,0,1]
	v_pk_mul_f32 v[22:23], v[160:161], v[122:123]
	v_pk_fma_f32 v[8:9], v[6:7], v[0:1], v[8:9] op_sel_hi:[1,0,1] neg_lo:[0,0,1] neg_hi:[0,0,1]
	v_pk_mul_f32 v[6:7], v[160:161], v[132:133]
	v_pk_fma_f32 v[68:69], v[14:15], v[0:1], v[68:69] op_sel_hi:[1,0,1] neg_lo:[0,0,1] neg_hi:[0,0,1]
	v_pk_fma_f32 v[16:17], v[16:17], v[0:1], v[12:13] op_sel_hi:[1,0,1] neg_lo:[0,0,1] neg_hi:[0,0,1]
	v_pk_mul_f32 v[134:135], v[52:53], v[52:53]
	v_pk_fma_f32 v[38:39], v[48:49], v[0:1], v[38:39] op_sel_hi:[1,0,1] neg_lo:[0,0,1] neg_hi:[0,0,1]
	v_pk_fma_f32 v[22:23], v[32:33], v[0:1], v[22:23] op_sel_hi:[1,0,1] neg_lo:[0,0,1] neg_hi:[0,0,1]
	v_pk_fma_f32 v[6:7], v[10:11], v[0:1], v[6:7] op_sel_hi:[1,0,1] neg_lo:[0,0,1] neg_hi:[0,0,1]
	v_add_f32_e32 v0, v136, v137
	v_add_f32_e32 v0, v0, v134
	v_pk_mul_f32 v[140:141], v[72:73], v[72:73]
	v_add_f32_e32 v0, v0, v135
	v_add_f32_e32 v0, v0, v140
	v_pk_mul_f32 v[138:139], v[50:51], v[50:51]
	v_add_f32_e32 v0, v0, v141
	v_add_f32_e32 v0, v0, v138
	v_pk_mul_f32 v[84:85], v[74:75], v[74:75]
	v_add_f32_e32 v0, v0, v139
	v_add_f32_e32 v0, v0, v84
	v_pk_mul_f32 v[86:87], v[54:55], v[54:55]
	v_add_f32_e32 v0, v0, v85
	v_add_f32_e32 v0, v0, v86
	v_pk_mul_f32 v[88:89], v[76:77], v[76:77]
	v_add_f32_e32 v0, v0, v87
	v_add_f32_e32 v0, v0, v88
	v_pk_mul_f32 v[90:91], v[56:57], v[56:57]
	v_add_f32_e32 v0, v0, v89
	v_add_f32_e32 v0, v0, v90
	v_pk_mul_f32 v[92:93], v[60:61], v[60:61]
	v_add_f32_e32 v0, v0, v91
	v_add_f32_e32 v0, v0, v92
	v_pk_mul_f32 v[94:95], v[58:59], v[58:59]
	v_add_f32_e32 v0, v0, v93
	v_add_f32_e32 v0, v0, v94
	v_lshlrev_b32_e32 v142, 2, v147
	v_pk_mul_f32 v[96:97], v[62:63], v[62:63]
	v_add_f32_e32 v0, v0, v95
	global_load_dwordx4 v[12:15], v142, s[16:17]
	v_add_f32_e32 v0, v0, v96
	v_pk_mul_f32 v[98:99], v[34:35], v[34:35]
	v_add_f32_e32 v0, v0, v97
	v_add_f32_e32 v0, v0, v98
	v_pk_mul_f32 v[100:101], v[64:65], v[64:65]
	v_add_f32_e32 v0, v0, v99
	v_add_f32_e32 v0, v0, v100
	v_pk_mul_f32 v[102:103], v[36:37], v[36:37]
	v_add_f32_e32 v0, v0, v101
	v_add_f32_e32 v0, v0, v102
	v_pk_mul_f32 v[104:105], v[46:47], v[46:47]
	v_add_f32_e32 v0, v0, v103
	v_add_f32_e32 v0, v0, v104
	v_pk_mul_f32 v[48:49], v[38:39], v[38:39]
	v_add_f32_e32 v0, v0, v105
	v_add_f32_e32 v0, v0, v48
	v_pk_mul_f32 v[108:109], v[42:43], v[42:43]
	v_add_f32_e32 v0, v0, v49
	v_add_f32_e32 v0, v0, v108
	v_pk_mul_f32 v[106:107], v[40:41], v[40:41]
	v_add_f32_e32 v0, v0, v109
	v_add_f32_e32 v0, v0, v106
	v_pk_mul_f32 v[112:113], v[44:45], v[44:45]
	v_add_f32_e32 v0, v0, v107
	v_add_f32_e32 v0, v0, v112
	v_pk_mul_f32 v[110:111], v[18:19], v[18:19]
	v_add_f32_e32 v0, v0, v113
	v_add_f32_e32 v0, v0, v110
	v_pk_mul_f32 v[116:117], v[26:27], v[26:27]
	v_add_f32_e32 v0, v0, v111
	v_add_f32_e32 v0, v0, v116
	v_pk_mul_f32 v[114:115], v[20:21], v[20:21]
	v_add_f32_e32 v0, v0, v117
	v_add_f32_e32 v0, v0, v114
	v_pk_mul_f32 v[30:31], v[28:29], v[28:29]
	v_add_f32_e32 v0, v0, v115
	v_add_f32_e32 v0, v0, v30
	v_pk_mul_f32 v[32:33], v[22:23], v[22:23]
	v_add_f32_e32 v0, v0, v31
	v_add_f32_e32 v0, v0, v32
	v_pk_mul_f32 v[120:121], v[24:25], v[24:25]
	v_add_f32_e32 v0, v0, v33
	v_add_f32_e32 v0, v0, v120
	v_pk_mul_f32 v[118:119], v[4:5], v[4:5]
	v_add_f32_e32 v0, v0, v121
	v_add_f32_e32 v0, v0, v118
	v_pk_mul_f32 v[124:125], v[8:9], v[8:9]
	v_add_f32_e32 v0, v0, v119
	v_add_f32_e32 v0, v0, v124
	v_pk_mul_f32 v[122:123], v[2:3], v[2:3]
	v_add_f32_e32 v0, v0, v125
	v_add_f32_e32 v0, v0, v122
	v_pk_mul_f32 v[10:11], v[6:7], v[6:7]
	v_add_f32_e32 v0, v0, v123
	v_add_f32_e32 v0, v0, v10
	v_pk_mul_f32 v[78:79], v[66:67], v[66:67]
	v_add_f32_e32 v0, v0, v11
	v_add_f32_e32 v0, v0, v78
	v_pk_mul_f32 v[80:81], v[68:69], v[68:69]
	v_add_f32_e32 v0, v0, v79
	v_add_f32_e32 v0, v0, v80
	v_pk_mul_f32 v[82:83], v[16:17], v[16:17]
	v_add_f32_e32 v0, v0, v81
	v_add_f32_e32 v0, v0, v82
	v_add_f32_e32 v0, v0, v83
	ds_bpermute_b32 v10, v171, v0
	global_load_dwordx4 v[80:83], v142, s[16:17] offset:32
	global_load_dwordx4 v[84:87], v142, s[16:17] offset:64
	global_load_dwordx4 v[88:91], v142, s[16:17] offset:96
	global_load_dwordx4 v[92:95], v142, s[16:17] offset:128
	global_load_dwordx4 v[96:99], v142, s[16:17] offset:160
	global_load_dwordx4 v[100:103], v142, s[16:17] offset:192
	global_load_dwordx4 v[104:107], v142, s[16:17] offset:224
	global_load_dwordx4 v[108:111], v142, s[16:17] offset:256
	global_load_dwordx4 v[112:115], v142, s[16:17] offset:288
	global_load_dwordx4 v[116:119], v142, s[16:17] offset:320
	global_load_dwordx4 v[120:123], v142, s[16:17] offset:352
	global_load_dwordx4 v[124:127], v142, s[16:17] offset:384
	global_load_dwordx4 v[128:131], v142, s[16:17] offset:416
	global_load_dwordx4 v[132:135], v142, s[16:17] offset:448
	global_load_dwordx4 v[136:139], v142, s[16:17] offset:480
	s_lshl_b32 s30, s5, 1
	s_waitcnt lgkmcnt(0)
	v_add_f32_e32 v0, v0, v10
	v_fmamk_f32 v0, v0, 0x3c000000, v172
	v_mul_f32_e32 v10, 0x4f800000, v0
	v_cmp_gt_f32_e32 vcc, s35, v0
	s_nop 1
	v_cndmask_b32_e32 v30, v0, v10, vcc
	v_sqrt_f32_e32 v31, v30
	v_lshlrev_b32_e32 v0, 11, v146
	v_lshl_add_u64 v[10:11], s[76:77], 0, v[0:1]
	v_lshl_add_u64 v[10:11], v[10:11], 0, s[30:31]
	v_add_u32_e32 v0, -1, v31
	v_fma_f32 v32, -v0, v31, v30
	v_cmp_ge_f32_e64 s[6:7], 0, v32
	v_add_u32_e32 v32, 1, v31
	s_nop 0
	v_cndmask_b32_e64 v0, v31, v0, s[6:7]
	v_fma_f32 v31, -v32, v31, v30
	v_cmp_lt_f32_e64 s[6:7], 0, v31
	s_nop 1
	v_cndmask_b32_e64 v0, v0, v32, s[6:7]
	v_mul_f32_e32 v31, 0x37800000, v0
	v_cndmask_b32_e32 v0, v0, v31, vcc
	v_cmp_class_f32_e32 vcc, v30, v170
	s_nop 1
	v_cndmask_b32_e32 v32, v0, v30, vcc
	v_div_scale_f32 v33, s[6:7], v32, v32, s1
	v_rcp_f32_e32 v48, v33
	v_lshlrev_b32_e32 v0, 1, v147
	v_lshl_add_u64 v[30:31], v[10:11], 0, v[0:1]
	v_fma_f32 v0, -v33, v48, 1.0
	v_fmac_f32_e32 v48, v0, v48
	v_div_scale_f32 v0, vcc, s1, v32, s1
	v_mul_f32_e32 v10, v0, v48
	v_fma_f32 v11, -v33, v10, v0
	v_fmac_f32_e32 v10, v11, v48
	v_fma_f32 v0, -v33, v10, v0
	v_div_fmas_f32 v0, v0, v48, v10
	v_div_fixup_f32 v0, v0, v32, s1
	s_waitcnt vmcnt(0)
	s_mov_b64 s[100:101], exec
	v_cmp_eq_u32_e64 s[98:99], 0, v208
	s_and_b64 s[98:99], s[100:101], s[98:99]
	s_mov_b64 exec, s[98:99]
	s_cbranch_execz .Lq5s_prompt
	v_mov_b32_e32 v251, 0
	v_mov_b32_e32 v249, 1
	global_atomic_add v250, v251, v165, s[52:53] sc0
; #define GASP __attribute__((address_space(1)))
;     ...
;             const float rms = 0.8f / sqrtf(ss * (1.f / 128.f) + LN_EPS);
;             const float* sg = p.in[16];
;             bf16_t* op = (bf16_t*)(ws + O_MIX) + (size_t)(rowq0 + r) * D + h * 128 + 4 * hi;
; #pragma unroll
;             for (int eb = 0; eb < 4; ++eb)
; #pragma unroll
;                 for (int g4 = 0; g4 < 4; ++g4) { const int e0 = eb * 32 + 8 * g4; const f32x4 gv = *(const GASP f32x4*)(sg + e0 + 4 * hi);
;                     u32x2 w; w.x = pk2(OT[eb][4 * g4] * rms * gv[0], OT[eb][4 * g4 + 1] * rms * gv[1]); w.y = pk2(OT[eb][4 * g4 + 2] * rms * gv[2], OT[eb][4 * g4 + 3] * rms * gv[3]);
;                     *(GASP u32x2*)(op + e0) = w; }
.Lq5s_prompt:
	s_mov_b64 exec, s[100:101]
	v_lshlrev_b32_e32 v202, 1, v147
	v_mov_b32_e32 v203, 0
	v_lshl_add_u64 v[206:207], v[30:31], 0, v[202:203]
	v_pk_mul_f32 v[202:203], v[70:71], v[0:1] op_sel_hi:[1,0]
	v_pk_mul_f32 v[204:205], v[52:53], v[0:1] op_sel_hi:[1,0]
	v_pk_mul_f32 v[202:203], v[12:13], v[202:203]
	v_pk_mul_f32 v[204:205], v[14:15], v[204:205]
	s_nop 0
	v_cvt_pk_bf16_f32 v194, v202, v203
	v_cvt_pk_bf16_f32 v195, v204, v205
	v_pk_mul_f32 v[202:203], v[72:73], v[0:1] op_sel_hi:[1,0]
	v_pk_mul_f32 v[204:205], v[50:51], v[0:1] op_sel_hi:[1,0]
	v_pk_mul_f32 v[202:203], v[80:81], v[202:203]
	v_pk_mul_f32 v[204:205], v[82:83], v[204:205]
	s_nop 0
	v_cvt_pk_bf16_f32 v196, v202, v203
	v_cvt_pk_bf16_f32 v197, v204, v205
	s_nop 1
	v_permlane32_swap_b32_e32 v194, v196
	v_permlane32_swap_b32_e32 v195, v197
	global_store_dwordx4 v[206:207], v[194:197], off
	v_pk_mul_f32 v[202:203], v[74:75], v[0:1] op_sel_hi:[1,0]
	v_pk_mul_f32 v[204:205], v[54:55], v[0:1] op_sel_hi:[1,0]
	v_pk_mul_f32 v[202:203], v[84:85], v[202:203]
	v_pk_mul_f32 v[204:205], v[86:87], v[204:205]
	s_nop 0
	v_cvt_pk_bf16_f32 v198, v202, v203
	v_cvt_pk_bf16_f32 v199, v204, v205
	v_pk_mul_f32 v[202:203], v[76:77], v[0:1] op_sel_hi:[1,0]
	v_pk_mul_f32 v[204:205], v[56:57], v[0:1] op_sel_hi:[1,0]
	v_pk_mul_f32 v[202:203], v[88:89], v[202:203]
	v_pk_mul_f32 v[204:205], v[90:91], v[204:205]
	s_nop 0
	v_cvt_pk_bf16_f32 v200, v202, v203
	v_cvt_pk_bf16_f32 v201, v204, v205
	s_nop 1
	v_permlane32_swap_b32_e32 v198, v200
	v_permlane32_swap_b32_e32 v199, v201
	global_store_dwordx4 v[206:207], v[198:201], off offset:32
	v_pk_mul_f32 v[202:203], v[60:61], v[0:1] op_sel_hi:[1,0]
	v_pk_mul_f32 v[204:205], v[58:59], v[0:1] op_sel_hi:[1,0]
	v_pk_mul_f32 v[202:203], v[92:93], v[202:203]
	v_pk_mul_f32 v[204:205], v[94:95], v[204:205]
	s_nop 0
	v_cvt_pk_bf16_f32 v194, v202, v203
	v_cvt_pk_bf16_f32 v195, v204, v205
	v_pk_mul_f32 v[202:203], v[62:63], v[0:1] op_sel_hi:[1,0]
	v_pk_mul_f32 v[204:205], v[34:35], v[0:1] op_sel_hi:[1,0]
	v_pk_mul_f32 v[202:203], v[96:97], v[202:203]
	v_pk_mul_f32 v[204:205], v[98:99], v[204:205]
	s_nop 0
	v_cvt_pk_bf16_f32 v196, v202, v203
	v_cvt_pk_bf16_f32 v197, v204, v205
	s_nop 1
	v_permlane32_swap_b32_e32 v194, v196
	v_permlane32_swap_b32_e32 v195, v197
	global_store_dwordx4 v[206:207], v[194:197], off offset:64
	v_pk_mul_f32 v[202:203], v[64:65], v[0:1] op_sel_hi:[1,0]
	v_pk_mul_f32 v[204:205], v[36:37], v[0:1] op_sel_hi:[1,0]
	v_pk_mul_f32 v[202:203], v[100:101], v[202:203]
	v_pk_mul_f32 v[204:205], v[102:103], v[204:205]
	s_nop 0
	v_cvt_pk_bf16_f32 v198, v202, v203
	v_cvt_pk_bf16_f32 v199, v204, v205
	v_pk_mul_f32 v[202:203], v[46:47], v[0:1] op_sel_hi:[1,0]
	v_pk_mul_f32 v[204:205], v[38:39], v[0:1] op_sel_hi:[1,0]
	v_pk_mul_f32 v[202:203], v[104:105], v[202:203]
	v_pk_mul_f32 v[204:205], v[106:107], v[204:205]
	s_nop 0
	v_cvt_pk_bf16_f32 v200, v202, v203
	v_cvt_pk_bf16_f32 v201, v204, v205
	s_nop 1
	v_permlane32_swap_b32_e32 v198, v200
	v_permlane32_swap_b32_e32 v199, v201
	global_store_dwordx4 v[206:207], v[198:201], off offset:96
	v_pk_mul_f32 v[202:203], v[42:43], v[0:1] op_sel_hi:[1,0]
	v_pk_mul_f32 v[204:205], v[40:41], v[0:1] op_sel_hi:[1,0]
	v_pk_mul_f32 v[202:203], v[108:109], v[202:203]
	v_pk_mul_f32 v[204:205], v[110:111], v[204:205]
	s_nop 0
	v_cvt_pk_bf16_f32 v194, v202, v203
	v_cvt_pk_bf16_f32 v195, v204, v205
	v_pk_mul_f32 v[202:203], v[44:45], v[0:1] op_sel_hi:[1,0]
	v_pk_mul_f32 v[204:205], v[18:19], v[0:1] op_sel_hi:[1,0]
	v_pk_mul_f32 v[202:203], v[112:113], v[202:203]
	v_pk_mul_f32 v[204:205], v[114:115], v[204:205]
	s_nop 0
	v_cvt_pk_bf16_f32 v196, v202, v203
	v_cvt_pk_bf16_f32 v197, v204, v205
	s_nop 1
	v_permlane32_swap_b32_e32 v194, v196
	v_permlane32_swap_b32_e32 v195, v197
	global_store_dwordx4 v[206:207], v[194:197], off offset:128
	v_pk_mul_f32 v[202:203], v[26:27], v[0:1] op_sel_hi:[1,0]
	v_pk_mul_f32 v[204:205], v[20:21], v[0:1] op_sel_hi:[1,0]
	v_pk_mul_f32 v[202:203], v[116:117], v[202:203]
	v_pk_mul_f32 v[204:205], v[118:119], v[204:205]
	s_nop 0
	v_cvt_pk_bf16_f32 v198, v202, v203
	v_cvt_pk_bf16_f32 v199, v204, v205
	v_pk_mul_f32 v[202:203], v[28:29], v[0:1] op_sel_hi:[1,0]
	v_pk_mul_f32 v[204:205], v[22:23], v[0:1] op_sel_hi:[1,0]
	v_pk_mul_f32 v[202:203], v[120:121], v[202:203]
	v_pk_mul_f32 v[204:205], v[122:123], v[204:205]
	s_nop 0
	v_cvt_pk_bf16_f32 v200, v202, v203
	v_cvt_pk_bf16_f32 v201, v204, v205
	s_nop 1
	v_permlane32_swap_b32_e32 v198, v200
	v_permlane32_swap_b32_e32 v199, v201
	global_store_dwordx4 v[206:207], v[198:201], off offset:160
	v_pk_mul_f32 v[202:203], v[24:25], v[0:1] op_sel_hi:[1,0]
	v_pk_mul_f32 v[204:205], v[4:5], v[0:1] op_sel_hi:[1,0]
	v_pk_mul_f32 v[202:203], v[124:125], v[202:203]
	v_pk_mul_f32 v[204:205], v[126:127], v[204:205]
	s_nop 0
	v_cvt_pk_bf16_f32 v194, v202, v203
	v_cvt_pk_bf16_f32 v195, v204, v205
	v_pk_mul_f32 v[202:203], v[8:9], v[0:1] op_sel_hi:[1,0]
	v_pk_mul_f32 v[204:205], v[2:3], v[0:1] op_sel_hi:[1,0]
	v_pk_mul_f32 v[202:203], v[128:129], v[202:203]
	v_pk_mul_f32 v[204:205], v[130:131], v[204:205]
	s_nop 0
	v_cvt_pk_bf16_f32 v196, v202, v203
	v_cvt_pk_bf16_f32 v197, v204, v205
	s_nop 1
	v_permlane32_swap_b32_e32 v194, v196
	v_permlane32_swap_b32_e32 v195, v197
	global_store_dwordx4 v[206:207], v[194:197], off offset:192
	v_pk_mul_f32 v[202:203], v[6:7], v[0:1] op_sel_hi:[1,0]
	v_pk_mul_f32 v[204:205], v[66:67], v[0:1] op_sel_hi:[1,0]
	v_pk_mul_f32 v[202:203], v[132:133], v[202:203]
	v_pk_mul_f32 v[204:205], v[134:135], v[204:205]
	s_nop 0
	v_cvt_pk_bf16_f32 v198, v202, v203
	v_cvt_pk_bf16_f32 v199, v204, v205
	v_pk_mul_f32 v[202:203], v[68:69], v[0:1] op_sel_hi:[1,0]
	v_pk_mul_f32 v[204:205], v[16:17], v[0:1] op_sel_hi:[1,0]
	v_pk_mul_f32 v[202:203], v[136:137], v[202:203]
	v_pk_mul_f32 v[204:205], v[138:139], v[204:205]
	s_nop 0
	v_cvt_pk_bf16_f32 v200, v202, v203
	v_cvt_pk_bf16_f32 v201, v204, v205
	s_nop 1
	v_permlane32_swap_b32_e32 v198, v200
	v_permlane32_swap_b32_e32 v199, v201
	global_store_dwordx4 v[206:207], v[198:201], off offset:224

; #define GASP __attribute__((address_space(1)))
;     ...
;         __syncthreads();
;         if (map == 0) {
;             ss = (SS[r] + SS[32 + r]) + (SS[64 + r] + SS[96 + r]);
;             const float rms = 0.8f / sqrtf(ss * (1.f / 128.f) + LN_EPS);
;             const float* sg = p.in[16];
;             bf16_t* op = (bf16_t*)(ws + O_MIX) + (size_t)(rowq0 + r) * D + h * 128 + sub * 32 + 4 * hi;
; #pragma unroll
;             for (int g4 = 0; g4 < 4; ++g4) { const f32x4 gv = *(const GASP f32x4*)(sg + sub * 32 + 8 * g4 + 4 * hi);
;                 u32x2 w; w.x = pk2(o16[4 * g4] * rms * gv[0], o16[4 * g4 + 1] * rms * gv[1]); w.y = pk2(o16[4 * g4 + 2] * rms * gv[2], o16[4 * g4 + 3] * rms * gv[3]);
;                 *(GASP u32x2*)(op + 8 * g4) = w; }
;         }
;         __syncthreads();
.LBB0_968:
	s_andn2_b64 vcc, exec, s[6:7]
	s_waitcnt lgkmcnt(0)
	s_barrier
	s_cbranch_vccnz .LBB0_868
	v_lshlrev_b64 v[12:13], 11, v[162:163]
	v_lshl_add_u64 v[12:13], s[76:77], 0, v[12:13]
	s_lshl_b32 s30, s4, 1
	v_lshl_add_u64 v[12:13], v[12:13], 0, s[30:31]
	s_lshl_b32 s30, s5, 5
	s_lshl_b32 s4, s5, 6
	s_lshl_b64 s[6:7], s[30:31], 2
	s_add_u32 s8, s16, s6
	s_addc_u32 s9, s17, s7
	v_lshlrev_b32_e32 v30, 2, v167
	global_load_dwordx4 v[24:27], v30, s[8:9]
	v_lshl_add_u32 v0, v175, 2, 0
	v_add_u32_e32 v0, 0x20800, v0
	ds_read2_b32 v[16:17], v0 offset1:32
	ds_read2_b32 v[20:21], v0 offset0:64 offset1:96
	s_mov_b32 s5, s31
	v_lshl_add_u64 v[12:13], v[12:13], 0, s[4:5]
	s_waitcnt lgkmcnt(1)
	v_mov_b32_e32 v28, v16
	s_waitcnt lgkmcnt(0)
	v_mov_b32_e32 v29, v20
	v_mov_b32_e32 v20, v17
	v_pk_add_f32 v[16:17], v[28:29], v[20:21]
	s_nop 0
	v_add_f32_e32 v0, v16, v17
	v_fmamk_f32 v0, v0, 0x3c000000, v172
	v_mul_f32_e32 v16, 0x4f800000, v0
	v_cmp_gt_f32_e32 vcc, s35, v0
	s_nop 1
	v_cndmask_b32_e32 v16, v0, v16, vcc
	v_sqrt_f32_e32 v17, v16
	v_lshlrev_b32_e32 v0, 1, v167
	v_lshl_add_u64 v[12:13], v[12:13], 0, v[0:1]
	v_add_u32_e32 v20, -1, v17
	v_add_u32_e32 v21, 1, v17
	v_fma_f32 v28, -v20, v17, v16
	v_fma_f32 v29, -v21, v17, v16
	v_cmp_ge_f32_e64 s[6:7], 0, v28
	s_nop 1
	v_cndmask_b32_e64 v17, v17, v20, s[6:7]
	v_cmp_lt_f32_e64 s[6:7], 0, v29
	s_nop 1
	v_cndmask_b32_e64 v17, v17, v21, s[6:7]
	v_mul_f32_e32 v20, 0x37800000, v17
	v_cndmask_b32_e32 v17, v17, v20, vcc
	v_cmp_class_f32_e32 vcc, v16, v170
	s_nop 1
	v_cndmask_b32_e32 v16, v17, v16, vcc
	v_div_scale_f32 v17, s[4:5], v16, v16, s1
	v_rcp_f32_e32 v20, v17
	v_div_scale_f32 v0, vcc, s1, v16, s1
	v_fma_f32 v21, -v17, v20, 1.0
	v_fmac_f32_e32 v20, v21, v20
	v_mul_f32_e32 v21, v0, v20
	v_fma_f32 v28, -v17, v21, v0
	v_fmac_f32_e32 v21, v28, v20
	v_fma_f32 v0, -v17, v21, v0
	v_div_fmas_f32 v0, v0, v20, v21
	v_div_fixup_f32 v0, v0, v16, s1
	v_pk_mul_f32 v[2:3], v[2:3], v[0:1] op_sel_hi:[1,0]
	v_pk_mul_f32 v[4:5], v[4:5], v[0:1] op_sel_hi:[1,0]
	v_pk_mul_f32 v[6:7], v[6:7], v[0:1] op_sel_hi:[1,0]
	v_pk_mul_f32 v[8:9], v[8:9], v[0:1] op_sel_hi:[1,0]
	s_waitcnt vmcnt(0)
	v_pk_mul_f32 v[2:3], v[24:25], v[2:3]
	v_pk_mul_f32 v[4:5], v[26:27], v[4:5]
	v_cvt_pk_bf16_f32 v2, v2, v3
	v_cvt_pk_bf16_f32 v3, v4, v5
	s_mov_b64 s[100:101], exec
	v_cmp_eq_u32_e64 s[98:99], 0, v208
	s_and_b64 s[98:99], s[100:101], s[98:99]
	s_mov_b64 exec, s[98:99]
	s_cbranch_execz .Lq5s_smp
	v_mov_b32_e32 v251, 0
	v_mov_b32_e32 v249, 1
	global_atomic_add v250, v251, v165, s[52:53] sc0
.Lq5s_smp:
	s_mov_b64 exec, s[100:101]
	global_store_dwordx2 v[12:13], v[2:3], off
	global_load_dwordx4 v[2:5], v30, s[8:9] offset:32
	s_waitcnt vmcnt(0)
	v_pk_mul_f32 v[2:3], v[2:3], v[6:7]
	v_pk_mul_f32 v[4:5], v[4:5], v[8:9]
	v_cvt_pk_bf16_f32 v2, v2, v3
	v_cvt_pk_bf16_f32 v3, v4, v5
	global_store_dwordx2 v[12:13], v[2:3], off offset:16
	global_load_dwordx4 v[2:5], v30, s[8:9] offset:64
	v_pk_mul_f32 v[6:7], v[10:11], v[0:1] op_sel_hi:[1,0]
	v_pk_mul_f32 v[8:9], v[14:15], v[0:1] op_sel_hi:[1,0]
	s_waitcnt vmcnt(0)
	v_pk_mul_f32 v[2:3], v[2:3], v[6:7]
	v_pk_mul_f32 v[4:5], v[4:5], v[8:9]
	v_cvt_pk_bf16_f32 v2, v2, v3
	v_cvt_pk_bf16_f32 v3, v4, v5
	global_store_dwordx2 v[12:13], v[2:3], off offset:32
	global_load_dwordx4 v[2:5], v30, s[8:9] offset:96
	v_pk_mul_f32 v[6:7], v[18:19], v[0:1] op_sel_hi:[1,0]
	v_pk_mul_f32 v[8:9], v[22:23], v[0:1] op_sel_hi:[1,0]
	s_waitcnt vmcnt(0)
	v_pk_mul_f32 v[2:3], v[6:7], v[2:3]
	v_pk_mul_f32 v[4:5], v[8:9], v[4:5]
	v_cvt_pk_bf16_f32 v2, v2, v3
	v_cvt_pk_bf16_f32 v3, v4, v5
	global_store_dwordx2 v[12:13], v[2:3], off offset:48
	s_branch .LBB0_868
